# chunk Q-conv: current-row load hoisted to join the tap loads (one wait per iteration); prep V staging: 6 first-touch loads batched before one wait
# speedup vs baseline: 1.0270x; 1.0033x over previous
.LBB0_631:
	v_mov_b32_e32 v137, 0
	v_mul_u32_u24_e32 v96, 0xaaab, v176
	v_lshrrev_b32_e32 v136, 20, v96
	v_mov_b64_e32 v[130:131], s[60:61]
	s_movk_i32 s20, 0xffe8
	v_lshl_add_u64 v[132:133], s[56:57], 0, v[136:137]
	v_mad_i32_i24 v96, v136, s20, v176
	v_mad_u64_u32 v[130:131], s[20:21], v132, s96, v[130:131]
	v_mov_b32_e32 v132, v131
	v_lshlrev_b32_e32 v134, 3, v96
	v_mad_u64_u32 v[132:133], s[20:21], v133, s96, v[132:133]
	v_ashrrev_i32_e32 v135, 31, v134
	v_mov_b32_e32 v131, v132
	v_lshl_add_u64 v[130:131], v[134:135], 1, v[130:131]
	global_load_dwordx4 v[100:103], v[130:131], off
	v_lshlrev_b32_e32 v96, 4, v96
	v_mad_u32_u24 v124, v136, s94, v96
	v_add_u32_e32 v99, 0x200, v176
	v_mul_u32_u24_e32 v96, 0xaaab, v99
	v_lshrrev_b32_e32 v136, 20, v96
	v_mov_b64_e32 v[130:131], s[60:61]
	s_movk_i32 s20, 0xffe8
	v_lshl_add_u64 v[132:133], s[56:57], 0, v[136:137]
	v_mad_i32_i24 v96, v136, s20, v99
	v_mad_u64_u32 v[130:131], s[20:21], v132, s96, v[130:131]
	v_mov_b32_e32 v132, v131
	v_lshlrev_b32_e32 v134, 3, v96
	v_mad_u64_u32 v[132:133], s[20:21], v133, s96, v[132:133]
	v_ashrrev_i32_e32 v135, 31, v134
	v_mov_b32_e32 v131, v132
	v_lshl_add_u64 v[130:131], v[134:135], 1, v[130:131]
	global_load_dwordx4 v[104:107], v[130:131], off
	v_lshlrev_b32_e32 v96, 4, v96
	v_mad_u32_u24 v125, v136, s94, v96
	v_add_u32_e32 v99, 0x400, v176
	v_mul_u32_u24_e32 v96, 0xaaab, v99
	v_lshrrev_b32_e32 v136, 20, v96
	v_mov_b64_e32 v[130:131], s[60:61]
	s_movk_i32 s20, 0xffe8
	v_lshl_add_u64 v[132:133], s[56:57], 0, v[136:137]
	v_mad_i32_i24 v96, v136, s20, v99
	v_mad_u64_u32 v[130:131], s[20:21], v132, s96, v[130:131]
	v_mov_b32_e32 v132, v131
	v_lshlrev_b32_e32 v134, 3, v96
	v_mad_u64_u32 v[132:133], s[20:21], v133, s96, v[132:133]
	v_ashrrev_i32_e32 v135, 31, v134
	v_mov_b32_e32 v131, v132
	v_lshl_add_u64 v[130:131], v[134:135], 1, v[130:131]
	global_load_dwordx4 v[108:111], v[130:131], off
	v_lshlrev_b32_e32 v96, 4, v96
	v_mad_u32_u24 v126, v136, s94, v96
	v_add_u32_e32 v99, 0x600, v176
	v_mul_u32_u24_e32 v96, 0xaaab, v99
	v_lshrrev_b32_e32 v136, 20, v96
	v_mov_b64_e32 v[130:131], s[60:61]
	s_movk_i32 s20, 0xffe8
	v_lshl_add_u64 v[132:133], s[56:57], 0, v[136:137]
	v_mad_i32_i24 v96, v136, s20, v99
	v_mad_u64_u32 v[130:131], s[20:21], v132, s96, v[130:131]
	v_mov_b32_e32 v132, v131
	v_lshlrev_b32_e32 v134, 3, v96
	v_mad_u64_u32 v[132:133], s[20:21], v133, s96, v[132:133]
	v_ashrrev_i32_e32 v135, 31, v134
	v_mov_b32_e32 v131, v132
	v_lshl_add_u64 v[130:131], v[134:135], 1, v[130:131]
	global_load_dwordx4 v[112:115], v[130:131], off
	v_lshlrev_b32_e32 v96, 4, v96
	v_mad_u32_u24 v127, v136, s94, v96
	v_add_u32_e32 v99, 0x800, v176
	v_mul_u32_u24_e32 v96, 0xaaab, v99
	v_lshrrev_b32_e32 v136, 20, v96
	v_mov_b64_e32 v[130:131], s[60:61]
	s_movk_i32 s20, 0xffe8
	v_lshl_add_u64 v[132:133], s[56:57], 0, v[136:137]
	v_mad_i32_i24 v96, v136, s20, v99
	v_mad_u64_u32 v[130:131], s[20:21], v132, s96, v[130:131]
	v_mov_b32_e32 v132, v131
	v_lshlrev_b32_e32 v134, 3, v96
	v_mad_u64_u32 v[132:133], s[20:21], v133, s96, v[132:133]
	v_ashrrev_i32_e32 v135, 31, v134
	v_mov_b32_e32 v131, v132
	v_lshl_add_u64 v[130:131], v[134:135], 1, v[130:131]
	global_load_dwordx4 v[116:119], v[130:131], off
	v_lshlrev_b32_e32 v96, 4, v96
	v_mad_u32_u24 v128, v136, s94, v96
	v_add_u32_e32 v99, 0xa00, v176
	v_mul_u32_u24_e32 v96, 0xaaab, v99
	v_lshrrev_b32_e32 v136, 20, v96
	v_mov_b64_e32 v[130:131], s[60:61]
	s_movk_i32 s20, 0xffe8
	v_lshl_add_u64 v[132:133], s[56:57], 0, v[136:137]
	v_mad_i32_i24 v96, v136, s20, v99
	v_mad_u64_u32 v[130:131], s[20:21], v132, s96, v[130:131]
	v_mov_b32_e32 v132, v131
	v_lshlrev_b32_e32 v134, 3, v96
	v_mad_u64_u32 v[132:133], s[20:21], v133, s96, v[132:133]
	v_ashrrev_i32_e32 v135, 31, v134
	v_mov_b32_e32 v131, v132
	v_lshl_add_u64 v[130:131], v[134:135], 1, v[130:131]
	global_load_dwordx4 v[120:123], v[130:131], off
	v_lshlrev_b32_e32 v96, 4, v96
	v_mad_u32_u24 v129, v136, s94, v96
	v_mov_b32_e32 v36, v136
	s_waitcnt vmcnt(0)
	ds_write_b128 v124, v[100:103]
	ds_write_b128 v125, v[104:107]
	ds_write_b128 v126, v[108:111]
	ds_write_b128 v127, v[112:115]
	ds_write_b128 v128, v[116:119]
	ds_write_b128 v129, v[120:123]
	s_or_b64 exec, exec, s[62:63]
	v_lshl_add_u64 v[0:1], v[40:41], 0, s[58:59]
	s_mov_b64 s[56:57], 0
	v_mov_b32_e32 v2, v53
	v_mov_b32_e32 v3, v52
	v_mov_b32_e32 v4, v51
	s_waitcnt lgkmcnt(0)
	s_barrier

.LBB0_1245:
	s_or_b64 exec, exec, s[58:59]
	s_waitcnt vmcnt(0) lgkmcnt(0)
	v_lshlrev_b32_e32 v37, 16, v12
	v_and_b32_e32 v12, 0xffff0000, v12
	v_fma_f32 v42, v20, v37, 0
	v_fma_f32 v37, v21, v12, 0
	v_lshlrev_b32_e32 v12, 16, v13
	v_fma_f32 v21, v22, v12, 0
	v_and_b32_e32 v12, 0xffff0000, v13
	v_fma_f32 v20, v23, v12, 0
	v_lshlrev_b32_e32 v12, 16, v14
	v_fma_f32 v16, v16, v12, 0
	v_and_b32_e32 v12, 0xffff0000, v14
	v_fma_f32 v14, v17, v12, 0
	v_lshlrev_b32_e32 v12, 16, v15
	v_fma_f32 v13, v18, v12, 0
	v_and_b32_e32 v12, 0xffff0000, v15
	v_lshlrev_b32_e32 v15, 16, v8
	v_and_b32_e32 v8, 0xffff0000, v8
	v_fmac_f32_e32 v37, v33, v8
	v_lshlrev_b32_e32 v8, 16, v9
	v_fmac_f32_e32 v21, v34, v8
	v_and_b32_e32 v8, 0xffff0000, v9
	v_fmac_f32_e32 v20, v35, v8
	v_lshlrev_b32_e32 v8, 16, v10
	v_fmac_f32_e32 v16, v28, v8
	v_and_b32_e32 v8, 0xffff0000, v10
	v_fmac_f32_e32 v14, v29, v8
	v_lshlrev_b32_e32 v8, 16, v11
	v_fma_f32 v12, v19, v12, 0
	v_fmac_f32_e32 v13, v30, v8
	v_and_b32_e32 v8, 0xffff0000, v11
	v_fmac_f32_e32 v12, v31, v8
	ds_read_b128 v[8:11], v41 offset:54272
	ds_read_b128 v[28:31], v41 offset:54288
	v_fmac_f32_e32 v42, v32, v15
	v_lshlrev_b32_e32 v15, 16, v24
	s_movk_i32 s14, 0x9ff
	s_waitcnt lgkmcnt(1)
	v_fmac_f32_e32 v42, v8, v15
	v_and_b32_e32 v8, 0xffff0000, v24
	v_fmac_f32_e32 v37, v9, v8
	v_lshlrev_b32_e32 v8, 16, v25
	v_fmac_f32_e32 v21, v10, v8
	v_and_b32_e32 v8, 0xffff0000, v25
	v_fmac_f32_e32 v20, v11, v8
	v_lshlrev_b32_e32 v8, 16, v26
	s_waitcnt lgkmcnt(0)
	v_fmac_f32_e32 v16, v28, v8
	v_and_b32_e32 v8, 0xffff0000, v26
	v_fmac_f32_e32 v14, v29, v8
	v_lshlrev_b32_e32 v8, 16, v27
	v_fmac_f32_e32 v13, v30, v8
	v_and_b32_e32 v8, 0xffff0000, v27
	v_fmac_f32_e32 v12, v31, v8
	v_mov_b64_e32 v[8:9], v[172:173]
	v_mov_b64_e32 v[10:11], v[174:175]
	ds_read_b128 v[22:25], v41 offset:55040
	s_waitcnt vmcnt(0) lgkmcnt(0)
	v_lshlrev_b32_e32 v15, 16, v8
	v_and_b32_e32 v8, 0xffff0000, v8
	v_fmac_f32_e32 v37, v23, v8
	v_lshlrev_b32_e32 v8, 16, v9
	v_fmac_f32_e32 v21, v24, v8
	v_and_b32_e32 v8, 0xffff0000, v9
	v_fmac_f32_e32 v42, v22, v15
	v_fmac_f32_e32 v20, v25, v8
	ds_read_b128 v[22:25], v41 offset:55056
	v_lshlrev_b32_e32 v8, 16, v10
	s_waitcnt lgkmcnt(0)
	v_fmac_f32_e32 v16, v22, v8
	v_and_b32_e32 v8, 0xffff0000, v10
	v_fmac_f32_e32 v14, v23, v8
	v_lshlrev_b32_e32 v8, 16, v11
	v_fmac_f32_e32 v13, v24, v8
	v_and_b32_e32 v8, 0xffff0000, v11
	v_fmac_f32_e32 v12, v25, v8
	v_mul_f32_e32 v8, 0xbfb8aa3b, v42
	v_exp_f32_e32 v8, v8
	s_nop 0
	v_add_f32_e32 v8, 1.0, v8
	v_div_scale_f32 v9, s[58:59], v8, v8, v42
	v_rcp_f32_e32 v10, v9
	s_nop 0
	v_fma_f32 v11, -v9, v10, 1.0
	v_fmac_f32_e32 v10, v11, v10
	v_div_scale_f32 v11, vcc, v42, v8, v42
	v_mul_f32_e32 v15, v11, v10
	v_fma_f32 v17, -v9, v15, v11
	v_fmac_f32_e32 v15, v17, v10
	v_fma_f32 v9, -v9, v15, v11
	v_div_fmas_f32 v9, v9, v10, v15
	v_div_fixup_f32 v8, v9, v8, v42
	v_mul_f32_e32 v9, 0xbfb8aa3b, v37
	v_exp_f32_e32 v9, v9
	s_nop 0
	v_add_f32_e32 v9, 1.0, v9
	v_div_scale_f32 v10, s[58:59], v9, v9, v37
	v_rcp_f32_e32 v11, v10
	s_nop 0
	v_fma_f32 v15, -v10, v11, 1.0
	v_fmac_f32_e32 v11, v15, v11
	v_div_scale_f32 v15, vcc, v37, v9, v37
	v_mul_f32_e32 v17, v15, v11
	v_fma_f32 v18, -v10, v17, v15
	v_fmac_f32_e32 v17, v18, v11
	v_fma_f32 v10, -v10, v17, v15
	v_div_fmas_f32 v10, v10, v11, v17
	v_div_fixup_f32 v9, v10, v9, v37
	v_mul_f32_e32 v10, 0xbfb8aa3b, v21
	v_exp_f32_e32 v10, v10
	v_cvt_pk_bf16_f32 v8, v8, v9
	s_nop 0
	v_add_f32_e32 v10, 1.0, v10
	v_div_scale_f32 v11, s[58:59], v10, v10, v21
	v_rcp_f32_e32 v15, v11
	s_nop 0
	v_fma_f32 v17, -v11, v15, 1.0
	v_fmac_f32_e32 v15, v17, v15
	v_div_scale_f32 v17, vcc, v21, v10, v21
	v_mul_f32_e32 v18, v17, v15
	v_fma_f32 v19, -v11, v18, v17
	v_fmac_f32_e32 v18, v19, v15
	v_fma_f32 v11, -v11, v18, v17
	v_div_fmas_f32 v11, v11, v15, v18
	v_div_fixup_f32 v10, v11, v10, v21
	v_mul_f32_e32 v11, 0xbfb8aa3b, v20
	v_exp_f32_e32 v11, v11
	s_nop 0
	v_add_f32_e32 v11, 1.0, v11
	v_div_scale_f32 v15, s[58:59], v11, v11, v20
	v_rcp_f32_e32 v17, v15
	s_nop 0
	v_fma_f32 v18, -v15, v17, 1.0
	v_fmac_f32_e32 v17, v18, v17
	v_div_scale_f32 v18, vcc, v20, v11, v20
	v_mul_f32_e32 v19, v18, v17
	v_fma_f32 v21, -v15, v19, v18
	v_fmac_f32_e32 v19, v21, v17
	v_fma_f32 v15, -v15, v19, v18
	v_div_fmas_f32 v15, v15, v17, v19
	v_div_fixup_f32 v11, v15, v11, v20
	v_mul_f32_e32 v15, 0xbfb8aa3b, v16
	v_exp_f32_e32 v15, v15
	v_cvt_pk_bf16_f32 v9, v10, v11
	s_nop 0
	v_add_f32_e32 v15, 1.0, v15
	v_div_scale_f32 v17, s[58:59], v15, v15, v16
	v_rcp_f32_e32 v18, v17
	s_nop 0
	v_fma_f32 v19, -v17, v18, 1.0
	v_fmac_f32_e32 v18, v19, v18
	v_div_scale_f32 v19, vcc, v16, v15, v16
	v_mul_f32_e32 v20, v19, v18
	v_fma_f32 v21, -v17, v20, v19
	v_fmac_f32_e32 v20, v21, v18
	v_fma_f32 v17, -v17, v20, v19
	v_div_fmas_f32 v17, v17, v18, v20
	v_div_fixup_f32 v15, v17, v15, v16
	v_mul_f32_e32 v16, 0xbfb8aa3b, v14
	v_exp_f32_e32 v16, v16
	s_nop 0
	v_add_f32_e32 v16, 1.0, v16
	v_div_scale_f32 v17, s[58:59], v16, v16, v14
	v_rcp_f32_e32 v18, v17
	s_nop 0
	v_fma_f32 v19, -v17, v18, 1.0
	v_fmac_f32_e32 v18, v19, v18
	v_div_scale_f32 v19, vcc, v14, v16, v14
	v_mul_f32_e32 v20, v19, v18
	v_fma_f32 v21, -v17, v20, v19
	v_fmac_f32_e32 v20, v21, v18
	v_fma_f32 v17, -v17, v20, v19
	v_div_fmas_f32 v17, v17, v18, v20
	v_div_fixup_f32 v14, v17, v16, v14
	v_mul_f32_e32 v16, 0xbfb8aa3b, v13
	v_exp_f32_e32 v16, v16
	v_cvt_pk_bf16_f32 v10, v15, v14
	s_nop 0
	v_add_f32_e32 v16, 1.0, v16
	v_div_scale_f32 v17, s[58:59], v16, v16, v13
	v_rcp_f32_e32 v18, v17
	s_nop 0
	v_fma_f32 v19, -v17, v18, 1.0
	v_fmac_f32_e32 v18, v19, v18
	v_div_scale_f32 v19, vcc, v13, v16, v13
	v_mul_f32_e32 v20, v19, v18
	v_fma_f32 v21, -v17, v20, v19
	v_fmac_f32_e32 v20, v21, v18
	v_fma_f32 v17, -v17, v20, v19
	v_div_fmas_f32 v17, v17, v18, v20
	v_div_fixup_f32 v13, v17, v16, v13
	v_mul_f32_e32 v16, 0xbfb8aa3b, v12
	v_exp_f32_e32 v16, v16
	s_nop 0
	v_add_f32_e32 v16, 1.0, v16
	v_div_scale_f32 v17, s[58:59], v16, v16, v12
	v_rcp_f32_e32 v18, v17
	s_nop 0
	v_fma_f32 v19, -v17, v18, 1.0
	v_fmac_f32_e32 v18, v19, v18
	v_div_scale_f32 v19, vcc, v12, v16, v12
	v_mul_f32_e32 v20, v19, v18
	v_fma_f32 v21, -v17, v20, v19
	v_fmac_f32_e32 v20, v21, v18
	v_fma_f32 v17, -v17, v20, v19
	v_div_fmas_f32 v17, v17, v18, v20
	v_div_fixup_f32 v12, v17, v16, v12
	v_cvt_pk_bf16_f32 v11, v13, v12
	v_lshlrev_b32_e32 v12, 1, v36
	v_mad_u32_u24 v0, v0, s33, v12
	ds_write_b128 v0, v[8:11]
	v_add_u32_e32 v0, 0x200, v40
	v_cmp_lt_u32_e32 vcc, s14, v40
	s_or_b64 s[56:57], vcc, s[56:57]
	v_mov_b32_e32 v40, v0
	s_andn2_b64 exec, exec, s[56:57]
	s_cbranch_execz .LBB0_1252
.LBB0_1246:
	v_mul_u32_u24_e32 v0, 0xaaab, v40
	v_lshrrev_b32_e32 v0, 20, v0
	v_mul_i32_i24_e32 v8, 0xffffffe8, v0
	v_add_lshl_u32 v36, v8, v40, 3
	v_lshl_add_u64 v[8:9], s[38:39], 0, v[0:1]
	v_mad_u64_u32 v[10:11], s[58:59], v8, s63, v[2:3]
	v_mov_b32_e32 v8, v11
	v_mad_u64_u32 v[8:9], s[58:59], v9, s63, v[8:9]
	v_mov_b32_e32 v11, v8
	v_ashrrev_i32_e32 v37, 31, v36
	v_add_u32_e32 v25, s17, v0
	v_lshl_add_u64 v[38:39], v[36:37], 1, v[10:11]
	global_load_dwordx4 v[172:175], v[38:39], off
	v_cmp_lt_u32_e32 vcc, 2, v25
	v_mov_b32_e32 v8, 0
	v_mov_b32_e32 v12, 0
	v_mov_b32_e32 v13, 0
	v_mov_b32_e32 v14, 0
	v_mov_b32_e32 v15, 0
	s_and_saveexec_b64 s[58:59], vcc
	s_cbranch_execz .LBB0_1248
	v_add_co_u32_e32 v10, vcc, 0xffffee00, v38
	s_nop 1
	v_addc_co_u32_e32 v11, vcc, -1, v39, vcc
	flat_load_dwordx4 v[12:15], v[10:11]
